# v83 with back-to-back polls (no s_sleep) in the XCD-local flag barriers
# speedup vs baseline: 1.0072x; 1.0072x over previous
.Lfb_poll_0:
	global_load_dword v5, v4, s[8:9] sc1
	s_waitcnt vmcnt(0)
	v_cmp_lt_u32_e32 vcc, v5, v0
	s_and_b64 vcc, exec, vcc
	s_cbranch_vccz .Lfb_done_0
	s_nop 0
	s_add_i32 s13, s13, 1
	s_cmp_lt_u32 s13, 0x8000
	s_cbranch_scc1 .Lfb_poll_0
